# scan chunk loop: output-norm parameter loads before the stage barrier; next chunk's loop-top mu loads issued before the end-of-chunk barrier when the loop continues
# baseline (speedup 1.0000x reference)
; DI float bflo(u32 v) { return __uint_as_float(v << 16); }
; DI float bfhi(u32 v) { return __uint_as_float(v & 0xffff0000u); }
; __device__ __forceinline__ void scan_item(const Params& p, int stream, int h, unsigned char* smem) {
;     ...
;   for (int tb = 0; tb < T; tb += 32) {
;     const int t0 = tb + 16 * hf;
;     {
;       float mu_r[4], mu_k[4], mu_v[4];
;       {
;         const float4 a4 = *(const float4*)(mu + hc), b4 = *(const float4*)(mu + 512 + hc), c4v = *(const float4*)(mu + 1024 + hc);
;         mu_r[0] = a4.x; mu_r[1] = a4.y; mu_r[2] = a4.z; mu_r[3] = a4.w;
;         mu_k[0] = b4.x; mu_k[1] = b4.y; mu_k[2] = b4.z; mu_k[3] = b4.w;
;         mu_v[0] = c4v.x; mu_v[1] = c4v.y; mu_v[2] = c4v.z; mu_v[3] = c4v.w;
;       }
;       const bool first = (t0 + et) == 0;
;       float rr[4], kk_[4], vv[4];
;       {
;         u32x2 c = g_cr, pv = first ? (u32x2){0u, 0u} : g_pr;
;         float cf[4] = {bflo(c[0]), bfhi(c[0]), bflo(c[1]), bfhi(c[1])};
;         float pf[4] = {bflo(pv[0]), bfhi(pv[0]), bflo(pv[1]), bfhi(pv[1])};
;         if (first && shift0) { float4 s4 = *(const float4*)(shift0 + hc); pf[0] = s4.x; pf[1] = s4.y; pf[2] = s4.z; pf[3] = s4.w; }
.Lsp_top:
	v_add_u32_e32 v170, s66, v196
	v_or_b32_e32 v0, v170, v98
	v_cmp_eq_u32_e32 vcc, 0, v0
	s_and_b64 s[0:1], vcc, s[54:55]
	s_waitcnt vmcnt(11)
	v_cndmask_b32_e64 v0, v103, 0, vcc
	v_cndmask_b32_e64 v1, v102, 0, vcc
	v_lshlrev_b32_e32 v76, 16, v1
	v_and_b32_e32 v77, 0xffff0000, v1
	v_lshlrev_b32_e32 v78, 16, v0
	v_and_b32_e32 v79, 0xffff0000, v0
	s_and_saveexec_b64 s[34:35], s[0:1]
	s_cbranch_execz .LBB0_1585
	global_load_dwordx4 v[76:79], v[120:121], off

; __device__ __forceinline__ void scan_item(const Params& p, int stream, int h, unsigned char* smem) {
;     ...
;     __syncthreads();
;     {
;       float lnw[4], lnb[4];
;       {
;         const float4 a4 = *(const float4*)(p.in[22] + hc), b4 = *(const float4*)(p.in[23] + hc);
;         lnw[0] = a4.x; lnw[1] = a4.y; lnw[2] = a4.z; lnw[3] = a4.w;
;         lnb[0] = b4.x; lnb[1] = b4.y; lnb[2] = b4.z; lnb[3] = b4.w;
;       }
;       float4 y4 = *(const float4*)(sY + et * 64 + ec);
;       float yy[4] = {y4.x, y4.y, y4.z, y4.w};
;       float s1 = row16_sum(yy[0] + yy[1] + yy[2] + yy[3]);
;       const float mean = s1 * (1.f / 64.f);
;       float s2 = 0.f;
; #pragma unroll
;       for (int j = 0; j < 4; ++j) { yy[j] -= mean; s2 += yy[j] * yy[j]; }
;       s2 = row16_sum(s2);
;       const float rs = __builtin_amdgcn_rsqf(s2 * (1.f / 64.f) + 64e-5f);
.LBB0_1608:
	s_or_b64 exec, exec, s[0:1]
	v_cmp_gt_i32_e32 vcc, s40, v170
	s_and_saveexec_b64 s[0:1], vcc
	global_load_dwordx4 v[240:243], v[160:161], off
	global_load_dwordx4 v[244:247], v[162:163], off
	s_mov_b64 exec, s[0:1]
	s_barrier
	ds_read_b128 v[68:71], v204 offset:28672
	s_waitcnt lgkmcnt(0)
	v_add_f32_e32 v0, v68, v69
	v_add_f32_e32 v0, v0, v70
	v_add_f32_e32 v0, v0, v71
	s_nop 1
	v_add_f32_dpp v0, v0, v0 quad_perm:[1,0,3,2] row_mask:0xf bank_mask:0xf bound_ctrl:1
	s_nop 1
	v_add_f32_dpp v0, v0, v0 quad_perm:[2,3,0,1] row_mask:0xf bank_mask:0xf bound_ctrl:1
	s_nop 1
	v_add_f32_dpp v0, v0, v0 row_half_mirror row_mask:0xf bank_mask:0xf bound_ctrl:1
	s_nop 1
	v_add_f32_dpp v0, v0, v0 row_mirror row_mask:0xf bank_mask:0xf bound_ctrl:1
	v_mul_f32_e32 v72, 0x3c800000, v0
	v_pk_add_f32 v[0:1], v[68:69], v[72:73] op_sel_hi:[1,0] neg_lo:[0,1] neg_hi:[0,1]
	v_pk_add_f32 v[68:69], v[70:71], v[72:73] op_sel_hi:[1,0] neg_lo:[0,1] neg_hi:[0,1]
	v_pk_mul_f32 v[70:71], v[0:1], v[0:1]
	v_pk_mul_f32 v[72:73], v[68:69], v[68:69]
	v_add_f32_e32 v3, v70, v71
	v_add_f32_e32 v3, v72, v3
	v_add_f32_e32 v3, v73, v3
	v_mov_b32_e32 v70, v2
	s_nop 0
	v_add_f32_dpp v3, v3, v3 quad_perm:[1,0,3,2] row_mask:0xf bank_mask:0xf bound_ctrl:1
	s_nop 1
	v_add_f32_dpp v3, v3, v3 quad_perm:[2,3,0,1] row_mask:0xf bank_mask:0xf bound_ctrl:1
	s_nop 1
	v_add_f32_dpp v3, v3, v3 row_half_mirror row_mask:0xf bank_mask:0xf bound_ctrl:1
	s_nop 1
	v_mov_b32_dpp v70, v3 row_mirror row_mask:0xf bank_mask:0xf
	s_and_saveexec_b64 s[0:1], vcc
	s_cbranch_execz .LBB0_1610
	v_add_f32_e32 v3, v3, v70
	ds_read_b32 v86, v99 offset:32768
	ds_read_b128 v[70:73], v204 offset:24576


; __device__ __forceinline__ void scan_item(const Params& p, int stream, int h, unsigned char* smem) {
;     ...
;       float mu_r[4], mu_k[4], mu_v[4];
;       {
;         const float4 a4 = *(const float4*)(mu + hc), b4 = *(const float4*)(mu + 512 + hc), c4v = *(const float4*)(mu + 1024 + hc);
;         mu_r[0] = a4.x; mu_r[1] = a4.y; mu_r[2] = a4.z; mu_r[3] = a4.w;
;         mu_k[0] = b4.x; mu_k[1] = b4.y; mu_k[2] = b4.z; mu_k[3] = b4.w;
;         mu_v[0] = c4v.x; mu_v[1] = c4v.y; mu_v[2] = c4v.z; mu_v[3] = c4v.w;
;       }
;     ...
;       const float rs = __builtin_amdgcn_rsqf(s2 * (1.f / 64.f) + 64e-5f);
;       const float rk = sRK[et];
;       float4 v4 = *(const float4*)(sV + et * 64 + ec);
;       float4 g4 = *(const float4*)(sG + et * 64 + ec);
;       const float vv[4] = {v4.x, v4.y, v4.z, v4.w}, gg[4] = {g4.x, g4.y, g4.z, g4.w};
;       float o[4];
; #pragma unroll
;       for (int j = 0; j < 4; ++j) o[j] = (yy[j] * rs * lnw[j] + lnb[j] + rk * vv[j]) * gg[j];
;       u32x2 ov = {pack2(o[0], o[1]), pack2(o[2], o[3])};
;       if (t0 < T) *(u32x2*)(MIX + (size_t)(row0 + t0 + et) * 1024 + hc) = ov;
;     }
;     __syncthreads();
;   }
	v_fmamk_f32 v3, v3, 0x3c800000, v173
	v_rsq_f32_e32 v84, v3
	v_ashrrev_i32_e32 v171, 31, v170
	v_pk_mul_f32 v[68:69], v[68:69], v[84:85] op_sel_hi:[1,0]
	v_pk_mul_f32 v[0:1], v[0:1], v[84:85] op_sel_hi:[1,0]
	s_waitcnt vmcnt(0)
	v_pk_fma_f32 v[68:69], v[68:69], v[242:243], v[246:247]
	ds_read_b128 v[80:83], v197 offset:20480
	v_pk_fma_f32 v[0:1], v[0:1], v[240:241], v[244:245]
	s_waitcnt lgkmcnt(0)
	v_pk_fma_f32 v[68:69], v[86:87], v[82:83], v[68:69] op_sel_hi:[0,1,1]
	v_pk_fma_f32 v[0:1], v[86:87], v[80:81], v[0:1] op_sel_hi:[0,1,1]
	v_pk_mul_f32 v[68:69], v[72:73], v[68:69]
	v_pk_mul_f32 v[0:1], v[70:71], v[0:1]
	v_cvt_pk_bf16_f32 v69, v68, v69
	v_cvt_pk_bf16_f32 v68, v0, v1
	v_lshl_add_u64 v[0:1], v[124:125], 0, v[170:171]
	v_lshlrev_b64 v[0:1], 11, v[0:1]
	v_lshl_add_u64 v[0:1], v[118:119], 0, v[0:1]
	global_store_dwordx2 v[0:1], v[68:69], off
.LBB0_1610:
	s_or_b64 exec, exec, s[0:1]
	s_and_b64 vcc, exec, s[60:61]
	s_cbranch_vccnz .Lsp_nold
	global_load_dwordx4 v[68:71], v[114:115], off
	global_load_dwordx4 v[80:83], v[112:113], off offset:2048
	global_load_dwordx4 v[72:75], v[112:113], off
.Lsp_nold:
	s_barrier
	s_cbranch_vccnz .LBB0_1612
	s_mov_b32 s66, s74
	s_branch .Lsp_top
